# diff far loops: first four K fragments of each 64-key sub-tile read into spare registers one sub-tile ahead (hides LDS latency at the second sub-tile)
# speedup vs baseline: 1.0022x; 1.0012x over previous
.LBB0_523:
	s_lshl_b32 s2, s30, 14
	s_and_b32 s2, s2, 0x4000
	s_cmpk_lt_u32 s30, 0x7f
	s_cselect_b64 s[16:17], -1, 0
	v_add_u32_e32 v158, s2, v190
	ds_read_b128 v[236:239], v158
	ds_read_b128 v[240:243], v158 offset:512
	ds_read_b128 v[244:247], v158 offset:4096
	ds_read_b128 v[248:251], v158 offset:4608
	v_add_u32_e32 v181, s2, v191
	s_lshl_b32 s31, s30, 7
	s_xor_b32 s2, s2, 0x4000
	s_addk_i32 s31, 0x80
	v_add_u32_e32 v193, s2, v189
	v_add_u32_e32 v194, s2, v188
	s_mov_b64 s[18:19], -1
	s_mov_b32 s34, 0
	s_branch .LBB0_525
.LBB0_524:
	ds_read_b128 v[236:239], v158 offset:1024
	ds_read_b128 v[240:243], v158 offset:1536
	ds_read_b128 v[244:247], v158 offset:5120
	ds_read_b128 v[248:251], v158 offset:5632
	v_pk_add_f32 v[76:77], v[170:171], 0 op_sel_hi:[1,0]
	v_pk_add_f32 v[78:79], v[178:179], 0 op_sel_hi:[1,0]
	v_pk_add_f32 v[76:77], v[168:169], v[76:77]
	v_pk_add_f32 v[78:79], v[108:109], v[78:79]
	v_pk_add_f32 v[76:77], v[166:167], v[76:77]
	v_pk_add_f32 v[78:79], v[104:105], v[78:79]
	v_pk_add_f32 v[76:77], v[164:165], v[76:77]
	v_pk_add_f32 v[66:67], v[66:67], v[78:79]
	v_pk_add_f32 v[76:77], v[126:127], v[76:77]
	v_pk_add_f32 v[66:67], v[118:119], v[66:67]
	v_pk_add_f32 v[76:77], v[174:175], v[76:77]
	v_pk_add_f32 v[66:67], v[116:117], v[66:67]
	v_pk_add_f32 v[76:77], v[172:173], v[76:77]
	v_pk_add_f32 v[66:67], v[106:107], v[66:67]
	v_pk_add_f32 v[76:77], v[96:97], v[76:77]
	v_pk_add_f32 v[66:67], v[68:69], v[66:67]
	v_pk_add_f32 v[76:77], v[176:177], v[76:77]
	v_pk_add_f32 v[66:67], v[120:121], v[66:67]
	v_pk_add_f32 v[76:77], v[114:115], v[76:77]
	v_pk_add_f32 v[66:67], v[86:87], v[66:67]
	v_pk_add_f32 v[76:77], v[112:113], v[76:77]
	v_pk_add_f32 v[66:67], v[84:85], v[66:67]
	v_pk_add_f32 v[76:77], v[110:111], v[76:77]
	v_pk_add_f32 v[66:67], v[82:83], v[66:67]
	v_pk_add_f32 v[68:69], v[102:103], v[76:77]
	v_pk_add_f32 v[66:67], v[80:81], v[66:67]
	v_pk_add_f32 v[68:69], v[100:101], v[68:69]
	v_pk_add_f32 v[66:67], v[74:75], v[66:67]
	v_pk_add_f32 v[68:69], v[98:99], v[68:69]
	v_pk_add_f32 v[66:67], v[72:73], v[66:67]
	v_pk_add_f32 v[64:65], v[64:65], v[68:69]
	v_pk_add_f32 v[66:67], v[70:71], v[66:67]
	s_xor_b64 s[2:3], s[18:19], -1
	v_pk_add_f32 v[64:65], v[64:65], v[66:67]
	s_mov_b32 s34, 1
	v_pk_add_f32 v[124:125], v[124:125], v[64:65]
	s_mov_b64 s[18:19], 0
	s_and_b64 vcc, exec, s[2:3]
	s_cbranch_vccnz .LBB0_529

.LBB0_527:
	s_lshl_b32 s8, s34, 10
	v_add_u32_e32 v88, s8, v158
	s_lshl_b32 s34, s34, 12
	v_add_u32_e32 v195, s34, v181
	s_waitcnt lgkmcnt(3)
	v_mfma_f32_32x32x16_bf16 v[92:107], v[236:239], v[128:131], 0
	s_and_b64 vcc, exec, s[2:3]
	s_waitcnt lgkmcnt(2)
	v_mfma_f32_32x32x16_bf16 v[64:79], v[240:243], v[128:131], 0
	s_waitcnt lgkmcnt(1)
	v_mfma_f32_32x32x16_bf16 v[92:107], v[244:247], v[132:135], v[92:107]
	s_waitcnt lgkmcnt(0)
	v_mfma_f32_32x32x16_bf16 v[64:79], v[248:251], v[132:135], v[64:79]
	ds_read_b128 v[80:83], v88 offset:8192
	ds_read_b128 v[84:87], v88 offset:8704
	s_nop 7
	v_exp_f32_e32 v171, v92
	v_exp_f32_e32 v169, v93
	v_exp_f32_e32 v167, v94
	v_exp_f32_e32 v165, v95
	v_exp_f32_e32 v127, v96
	v_exp_f32_e32 v175, v97
	s_waitcnt lgkmcnt(1)
	v_mfma_f32_32x32x16_bf16 v[108:123], v[80:83], v[136:139], 0
	ds_read_b128 v[80:83], v88 offset:12288
	ds_read_b128 v[176:179], v88 offset:12800
	v_exp_f32_e32 v173, v98
	v_exp_f32_e32 v97, v99
	v_cvt_pk_bf16_f32 v196, v171, v169
	v_cvt_pk_bf16_f32 v197, v167, v165
	v_cvt_pk_bf16_f32 v198, v127, v175
	v_cvt_pk_bf16_f32 v199, v173, v97
	s_waitcnt lgkmcnt(1)
	v_mfma_f32_32x32x16_bf16 v[108:123], v[80:83], v[140:143], v[108:123]
	ds_read_b64_tr_b16 v[200:201], v195 offset:32768
	ds_read_b64_tr_b16 v[202:203], v195 offset:33280
	ds_read_b64_tr_b16 v[204:205], v195 offset:33792
	ds_read_b64_tr_b16 v[206:207], v195 offset:34304
	ds_read_b64_tr_b16 v[208:209], v195 offset:40960
	ds_read_b64_tr_b16 v[210:211], v195 offset:41472
	v_exp_f32_e32 v99, v106
	ds_read_b64_tr_b16 v[216:217], v195 offset:41984
	ds_read_b64_tr_b16 v[218:219], v195 offset:42496
	v_exp_f32_e32 v67, v67
	s_nop 1
	v_exp_f32_e32 v170, v108
	v_mfma_f32_32x32x16_bf16 v[80:95], v[84:87], v[136:139], 0
	v_exp_f32_e32 v168, v109
	v_exp_f32_e32 v166, v110
	v_exp_f32_e32 v164, v111
	v_exp_f32_e32 v126, v112
	v_exp_f32_e32 v174, v113
	v_exp_f32_e32 v172, v114
	v_exp_f32_e32 v96, v115
	v_cvt_pk_bf16_f32 v212, v170, v168
	v_cvt_pk_bf16_f32 v213, v166, v164
	v_cvt_pk_bf16_f32 v214, v126, v174
	v_cvt_pk_bf16_f32 v215, v172, v96
	s_waitcnt lgkmcnt(8)
	v_mfma_f32_32x32x16_bf16 v[80:95], v[176:179], v[140:143], v[80:95]
	v_exp_f32_e32 v179, v64
	v_exp_f32_e32 v109, v65
	v_exp_f32_e32 v177, v100
	v_exp_f32_e32 v115, v101
	v_exp_f32_e32 v113, v102
	v_exp_f32_e32 v111, v103
	v_exp_f32_e32 v103, v104
	v_exp_f32_e32 v101, v105
	v_exp_f32_e32 v65, v107
	v_exp_f32_e32 v176, v116
	v_exp_f32_e32 v114, v117
	v_exp_f32_e32 v112, v118
	v_exp_f32_e32 v110, v119
	v_exp_f32_e32 v102, v120
	v_exp_f32_e32 v100, v121
	v_exp_f32_e32 v98, v122
	v_exp_f32_e32 v64, v123
	s_waitcnt lgkmcnt(6)
	v_mfma_f32_32x32x16_bf16 v[48:63], v[196:199], v[200:203], v[48:63]
	v_cvt_pk_bf16_f32 v120, v176, v114
	v_cvt_pk_bf16_f32 v121, v112, v110
	v_cvt_pk_bf16_f32 v122, v102, v100
	v_cvt_pk_bf16_f32 v123, v98, v64
	v_exp_f32_e32 v105, v66
	v_exp_f32_e32 v119, v68
	v_exp_f32_e32 v117, v69
	v_mfma_f32_32x32x16_bf16 v[16:31], v[212:215], v[200:203], v[16:31]
	v_exp_f32_e32 v107, v70
	v_exp_f32_e32 v69, v71
	v_exp_f32_e32 v178, v80
	v_exp_f32_e32 v108, v81
	v_exp_f32_e32 v104, v82
	v_exp_f32_e32 v66, v83
	v_exp_f32_e32 v118, v84
	s_waitcnt lgkmcnt(2)
	v_mfma_f32_32x32x16_bf16 v[32:47], v[196:199], v[208:211], v[32:47]
	v_cvt_pk_bf16_f32 v196, v177, v115
	v_cvt_pk_bf16_f32 v197, v113, v111
	v_cvt_pk_bf16_f32 v198, v103, v101
	v_cvt_pk_bf16_f32 v199, v99, v65
	v_exp_f32_e32 v116, v85
	v_exp_f32_e32 v106, v86
	v_exp_f32_e32 v68, v87
	v_mfma_f32_32x32x16_bf16 v[0:15], v[212:215], v[208:211], v[0:15]
	ds_read_b64_tr_b16 v[80:81], v195 offset:34816
	ds_read_b64_tr_b16 v[82:83], v195 offset:35328
	v_cvt_pk_bf16_f32 v208, v178, v108
	v_cvt_pk_bf16_f32 v209, v104, v66
	v_cvt_pk_bf16_f32 v210, v118, v116
	v_cvt_pk_bf16_f32 v211, v106, v68
	ds_read_b64_tr_b16 v[200:201], v195 offset:35840
	ds_read_b64_tr_b16 v[202:203], v195 offset:36352
	v_exp_f32_e32 v87, v73
	v_mfma_f32_32x32x16_bf16 v[48:63], v[196:199], v[204:207], v[48:63]
	v_exp_f32_e32 v85, v74
	v_exp_f32_e32 v73, v78
	v_exp_f32_e32 v71, v79
	v_exp_f32_e32 v86, v89
	v_exp_f32_e32 v84, v90
	v_exp_f32_e32 v74, v93
	v_exp_f32_e32 v70, v95
	v_mfma_f32_32x32x16_bf16 v[16:31], v[120:123], v[204:207], v[16:31]
	ds_read_b64_tr_b16 v[204:205], v195 offset:43008
	ds_read_b64_tr_b16 v[206:207], v195 offset:43520
	ds_read_b64_tr_b16 v[212:213], v195 offset:44032
	ds_read_b64_tr_b16 v[214:215], v195 offset:44544
	v_cvt_pk_bf16_f32 v79, v73, v71
	s_waitcnt lgkmcnt(8)
	v_mfma_f32_32x32x16_bf16 v[32:47], v[196:199], v[216:219], v[32:47]
	v_cvt_pk_bf16_f32 v196, v179, v109
	v_cvt_pk_bf16_f32 v197, v105, v67
	v_cvt_pk_bf16_f32 v198, v119, v117
	v_cvt_pk_bf16_f32 v199, v107, v69
	v_mfma_f32_32x32x16_bf16 v[0:15], v[120:123], v[216:219], v[0:15]
	v_exp_f32_e32 v121, v72
	v_exp_f32_e32 v120, v88
	v_exp_f32_e32 v72, v94
	v_cvt_pk_bf16_f32 v88, v120, v86
	s_waitcnt lgkmcnt(6)
	v_mfma_f32_32x32x16_bf16 v[48:63], v[196:199], v[80:83], v[48:63]
	v_mfma_f32_32x32x16_bf16 v[16:31], v[208:211], v[80:83], v[16:31]
	v_exp_f32_e32 v83, v75
	v_exp_f32_e32 v81, v76
	v_exp_f32_e32 v75, v77
	v_exp_f32_e32 v82, v91
	v_exp_f32_e32 v80, v92
	v_cvt_pk_bf16_f32 v76, v121, v87
	v_cvt_pk_bf16_f32 v77, v85, v83
	s_waitcnt lgkmcnt(2)
	v_mfma_f32_32x32x16_bf16 v[32:47], v[196:199], v[204:207], v[32:47]
	v_cvt_pk_bf16_f32 v78, v81, v75
	v_cvt_pk_bf16_f32 v89, v84, v82
	v_cvt_pk_bf16_f32 v90, v80, v74
	v_cvt_pk_bf16_f32 v91, v72, v70
	v_mfma_f32_32x32x16_bf16 v[0:15], v[208:211], v[204:207], v[0:15]
	v_mfma_f32_32x32x16_bf16 v[48:63], v[76:79], v[200:203], v[48:63]
	s_waitcnt lgkmcnt(0)
	v_mfma_f32_32x32x16_bf16 v[32:47], v[76:79], v[212:215], v[32:47]
	v_mfma_f32_32x32x16_bf16 v[16:31], v[88:91], v[200:203], v[16:31]
	v_mfma_f32_32x32x16_bf16 v[0:15], v[88:91], v[212:215], v[0:15]
	s_cbranch_vccnz .LBB0_524
	v_add_u32_e32 v77, s8, v194
	v_add_u32_e32 v76, s34, v193
	s_waitcnt vmcnt(1)
	ds_write_b128 v77, v[144:147]
	s_waitcnt vmcnt(0)
	ds_write_b128 v76, v[148:151] offset:32768
	s_branch .LBB0_524

.LBB0_543:
	s_lshl_b32 s2, s28, 14
	s_and_b32 s2, s2, 0x4000
	s_cmpk_lg_i32 s28, 0x7f
	s_cselect_b64 s[16:17], -1, 0
	v_add_u32_e32 v158, s2, v190
	ds_read_b128 v[236:239], v158
	ds_read_b128 v[240:243], v158 offset:512
	ds_read_b128 v[244:247], v158 offset:4096
	ds_read_b128 v[248:251], v158 offset:4608
	v_add_u32_e32 v180, s2, v191
	s_lshl_b32 s15, s28, 7
	s_xor_b32 s2, s2, 0x4000
	s_addk_i32 s15, 0x80
	v_add_u32_e32 v181, s2, v189
	v_add_u32_e32 v192, s2, v188
	s_mov_b32 s29, 0
	s_mov_b64 s[18:19], -1
	s_branch .LBB0_545
.LBB0_544:
	ds_read_b128 v[236:239], v158 offset:1024
	ds_read_b128 v[240:243], v158 offset:1536
	ds_read_b128 v[244:247], v158 offset:5120
	ds_read_b128 v[248:251], v158 offset:5632
	v_pk_add_f32 v[76:77], v[166:167], 0 op_sel_hi:[1,0]
	v_pk_add_f32 v[78:79], v[176:177], 0 op_sel_hi:[1,0]
	v_pk_add_f32 v[76:77], v[174:175], v[76:77]
	v_pk_add_f32 v[78:79], v[178:179], v[78:79]
	v_pk_add_f32 v[76:77], v[168:169], v[76:77]
	v_pk_add_f32 v[78:79], v[108:109], v[78:79]
	v_pk_add_f32 v[76:77], v[172:173], v[76:77]
	v_pk_add_f32 v[66:67], v[66:67], v[78:79]
	v_pk_add_f32 v[76:77], v[98:99], v[76:77]
	v_pk_add_f32 v[66:67], v[110:111], v[66:67]
	v_pk_add_f32 v[76:77], v[170:171], v[76:77]
	v_pk_add_f32 v[66:67], v[122:123], v[66:67]
	v_pk_add_f32 v[76:77], v[100:101], v[76:77]
	v_pk_add_f32 v[66:67], v[120:121], v[66:67]
	v_pk_add_f32 v[76:77], v[96:97], v[76:77]
	v_pk_add_f32 v[66:67], v[68:69], v[66:67]
	v_pk_add_f32 v[68:69], v[118:119], v[76:77]
	v_pk_add_f32 v[66:67], v[124:125], v[66:67]
	v_pk_add_f32 v[68:69], v[116:117], v[68:69]
	v_pk_add_f32 v[66:67], v[86:87], v[66:67]
	v_pk_add_f32 v[68:69], v[114:115], v[68:69]
	v_pk_add_f32 v[66:67], v[84:85], v[66:67]
	v_pk_add_f32 v[68:69], v[112:113], v[68:69]
	v_pk_add_f32 v[66:67], v[82:83], v[66:67]
	v_pk_add_f32 v[68:69], v[106:107], v[68:69]
	v_pk_add_f32 v[66:67], v[80:81], v[66:67]
	v_pk_add_f32 v[68:69], v[104:105], v[68:69]
	v_pk_add_f32 v[66:67], v[74:75], v[66:67]
	v_pk_add_f32 v[68:69], v[102:103], v[68:69]
	v_pk_add_f32 v[66:67], v[72:73], v[66:67]
	v_pk_add_f32 v[64:65], v[64:65], v[68:69]
	v_pk_add_f32 v[66:67], v[70:71], v[66:67]
	s_xor_b64 s[2:3], s[18:19], -1
	v_pk_add_f32 v[64:65], v[64:65], v[66:67]
	s_mov_b32 s29, 1
	v_pk_add_f32 v[164:165], v[164:165], v[64:65]
	s_mov_b64 s[18:19], 0
	s_and_b64 vcc, exec, s[2:3]
	s_cbranch_vccnz .LBB0_549

.LBB0_547:
	s_lshl_b32 s8, s29, 10
	v_add_u32_e32 v88, s8, v158
	s_lshl_b32 s29, s29, 12
	v_add_u32_e32 v193, s29, v180
	s_waitcnt lgkmcnt(3)
	v_mfma_f32_32x32x16_bf16 v[96:111], v[236:239], v[128:131], 0
	s_and_b64 vcc, exec, s[2:3]
	s_waitcnt lgkmcnt(2)
	v_mfma_f32_32x32x16_bf16 v[64:79], v[240:243], v[128:131], 0
	s_waitcnt lgkmcnt(1)
	v_mfma_f32_32x32x16_bf16 v[96:111], v[244:247], v[132:135], v[96:111]
	s_waitcnt lgkmcnt(0)
	v_mfma_f32_32x32x16_bf16 v[64:79], v[248:251], v[132:135], v[64:79]
	ds_read_b128 v[80:83], v88 offset:8192
	ds_read_b128 v[84:87], v88 offset:8704
	s_nop 7
	v_exp_f32_e32 v167, v96
	v_exp_f32_e32 v175, v97
	v_exp_f32_e32 v169, v98
	v_exp_f32_e32 v173, v99
	v_exp_f32_e32 v99, v100
	v_exp_f32_e32 v171, v101
	s_waitcnt lgkmcnt(1)
	v_mfma_f32_32x32x16_bf16 v[112:127], v[80:83], v[136:139], 0
	ds_read_b128 v[80:83], v88 offset:12288
	ds_read_b128 v[176:179], v88 offset:12800
	v_exp_f32_e32 v101, v102
	v_exp_f32_e32 v97, v103
	ds_read_b64_tr_b16 v[194:195], v193 offset:32768
	ds_read_b64_tr_b16 v[196:197], v193 offset:33280
	ds_read_b64_tr_b16 v[198:199], v193 offset:33792
	ds_read_b64_tr_b16 v[200:201], v193 offset:34304
	ds_read_b64_tr_b16 v[202:203], v193 offset:40960
	ds_read_b64_tr_b16 v[204:205], v193 offset:41472
	v_exp_f32_e32 v103, v110
	s_waitcnt lgkmcnt(7)
	v_mfma_f32_32x32x16_bf16 v[112:127], v[80:83], v[140:143], v[112:127]
	ds_read_b64_tr_b16 v[210:211], v193 offset:41984
	ds_read_b64_tr_b16 v[212:213], v193 offset:42496
	v_exp_f32_e32 v67, v67
	v_mfma_f32_32x32x16_bf16 v[80:95], v[84:87], v[136:139], 0
	s_nop 7
	v_exp_f32_e32 v166, v112
	v_exp_f32_e32 v174, v113
	v_exp_f32_e32 v168, v114
	v_exp_f32_e32 v172, v115
	v_exp_f32_e32 v98, v116
	v_exp_f32_e32 v170, v117
	v_exp_f32_e32 v100, v118
	v_exp_f32_e32 v96, v119
	v_cvt_pk_bf16_f32 v112, v167, v175
	v_cvt_pk_bf16_f32 v113, v169, v173
	v_cvt_pk_bf16_f32 v114, v99, v171
	v_cvt_pk_bf16_f32 v115, v101, v97
	v_cvt_pk_bf16_f32 v206, v166, v174
	v_cvt_pk_bf16_f32 v207, v168, v172
	v_cvt_pk_bf16_f32 v208, v98, v170
	v_cvt_pk_bf16_f32 v209, v100, v96
	s_waitcnt lgkmcnt(8)
	v_mfma_f32_32x32x16_bf16 v[80:95], v[176:179], v[140:143], v[80:95]
	v_exp_f32_e32 v179, v65
	v_exp_f32_e32 v119, v104
	v_exp_f32_e32 v117, v105
	v_exp_f32_e32 v105, v109
	v_exp_f32_e32 v65, v111
	v_exp_f32_e32 v177, v64
	v_exp_f32_e32 v118, v120
	s_waitcnt lgkmcnt(6)
	v_mfma_f32_32x32x16_bf16 v[0:15], v[112:115], v[194:197], v[0:15]
	v_exp_f32_e32 v116, v121
	v_exp_f32_e32 v104, v125
	v_exp_f32_e32 v102, v126
	v_exp_f32_e32 v64, v127
	v_exp_f32_e32 v109, v66
	v_exp_f32_e32 v111, v68
	v_exp_f32_e32 v121, v70
	s_waitcnt lgkmcnt(2)
	v_mfma_f32_32x32x16_bf16 v[16:31], v[112:115], v[202:205], v[16:31]
	v_exp_f32_e32 v115, v106
	v_exp_f32_e32 v113, v107
	v_exp_f32_e32 v107, v108
	v_exp_f32_e32 v114, v122
	v_exp_f32_e32 v112, v123
	v_exp_f32_e32 v106, v124
	v_cvt_pk_bf16_f32 v124, v118, v116
	v_mfma_f32_32x32x16_bf16 v[32:47], v[206:209], v[194:197], v[32:47]
	v_cvt_pk_bf16_f32 v194, v119, v117
	v_cvt_pk_bf16_f32 v195, v115, v113
	v_cvt_pk_bf16_f32 v196, v107, v105
	v_cvt_pk_bf16_f32 v197, v103, v65
	v_cvt_pk_bf16_f32 v125, v114, v112
	v_cvt_pk_bf16_f32 v126, v106, v104
	v_cvt_pk_bf16_f32 v127, v102, v64
	v_mfma_f32_32x32x16_bf16 v[48:63], v[206:209], v[202:205], v[48:63]
	v_exp_f32_e32 v123, v69
	v_exp_f32_e32 v69, v71
	v_exp_f32_e32 v176, v80
	v_exp_f32_e32 v178, v81
	v_exp_f32_e32 v108, v82
	v_exp_f32_e32 v66, v83
	v_exp_f32_e32 v110, v84
	v_mfma_f32_32x32x16_bf16 v[0:15], v[194:197], v[198:201], v[0:15]
	v_exp_f32_e32 v122, v85
	v_exp_f32_e32 v120, v86
	v_exp_f32_e32 v68, v87
	v_cvt_pk_bf16_f32 v80, v177, v179
	v_cvt_pk_bf16_f32 v81, v109, v67
	v_cvt_pk_bf16_f32 v82, v111, v123
	v_cvt_pk_bf16_f32 v83, v121, v69
	s_waitcnt lgkmcnt(0)
	v_mfma_f32_32x32x16_bf16 v[16:31], v[194:197], v[210:213], v[16:31]
	ds_read_b64_tr_b16 v[194:195], v193 offset:34816
	ds_read_b64_tr_b16 v[196:197], v193 offset:35328
	v_cvt_pk_bf16_f32 v206, v176, v178
	v_cvt_pk_bf16_f32 v207, v108, v66
	v_cvt_pk_bf16_f32 v208, v110, v122
	v_cvt_pk_bf16_f32 v209, v120, v68
	v_exp_f32_e32 v87, v73
	v_exp_f32_e32 v85, v74
	v_mfma_f32_32x32x16_bf16 v[32:47], v[124:127], v[198:201], v[32:47]
	ds_read_b64_tr_b16 v[198:199], v193 offset:35840
	ds_read_b64_tr_b16 v[200:201], v193 offset:36352
	ds_read_b64_tr_b16 v[202:203], v193 offset:43008
	ds_read_b64_tr_b16 v[204:205], v193 offset:43520
	v_exp_f32_e32 v73, v78
	v_exp_f32_e32 v71, v79
	v_exp_f32_e32 v86, v89
	v_exp_f32_e32 v84, v90
	v_exp_f32_e32 v74, v93
	v_mfma_f32_32x32x16_bf16 v[48:63], v[124:127], v[210:213], v[48:63]
	v_exp_f32_e32 v125, v72
	v_exp_f32_e32 v124, v88
	v_exp_f32_e32 v72, v94
	v_exp_f32_e32 v70, v95
	ds_read_b64_tr_b16 v[210:211], v193 offset:44032
	ds_read_b64_tr_b16 v[212:213], v193 offset:44544
	v_cvt_pk_bf16_f32 v79, v73, v71
	v_cvt_pk_bf16_f32 v88, v124, v86
	s_waitcnt lgkmcnt(6)
	v_mfma_f32_32x32x16_bf16 v[0:15], v[80:83], v[194:197], v[0:15]
	s_waitcnt lgkmcnt(2)
	v_mfma_f32_32x32x16_bf16 v[16:31], v[80:83], v[202:205], v[16:31]
	v_exp_f32_e32 v83, v75
	v_exp_f32_e32 v81, v76
	v_exp_f32_e32 v75, v77
	v_exp_f32_e32 v82, v91
	v_exp_f32_e32 v80, v92
	v_cvt_pk_bf16_f32 v76, v125, v87
	v_cvt_pk_bf16_f32 v77, v85, v83
	v_mfma_f32_32x32x16_bf16 v[32:47], v[206:209], v[194:197], v[32:47]
	v_cvt_pk_bf16_f32 v78, v81, v75
	v_cvt_pk_bf16_f32 v89, v84, v82
	v_cvt_pk_bf16_f32 v90, v80, v74
	v_cvt_pk_bf16_f32 v91, v72, v70
	v_mfma_f32_32x32x16_bf16 v[48:63], v[206:209], v[202:205], v[48:63]
	v_mfma_f32_32x32x16_bf16 v[0:15], v[76:79], v[198:201], v[0:15]
	s_waitcnt lgkmcnt(0)
	v_mfma_f32_32x32x16_bf16 v[16:31], v[76:79], v[210:213], v[16:31]
	v_mfma_f32_32x32x16_bf16 v[32:47], v[88:91], v[198:201], v[32:47]
	v_mfma_f32_32x32x16_bf16 v[48:63], v[88:91], v[210:213], v[48:63]
	s_cbranch_vccnz .LBB0_544
	v_add_u32_e32 v77, s8, v192
	v_add_u32_e32 v76, s29, v181
	s_waitcnt vmcnt(1)
	ds_write_b128 v77, v[144:147]
	s_waitcnt vmcnt(0)
	ds_write_b128 v76, v[148:151] offset:32768
	s_branch .LBB0_544

.LBB0_1235:
	s_lshl_b32 s4, s34, 14
	s_and_b32 s4, s4, 0x4000
	s_cmpk_lt_u32 s34, 0x7f
	s_cselect_b64 s[18:19], -1, 0
	v_add_u32_e32 v158, s4, v190
	ds_read_b128 v[236:239], v158
	ds_read_b128 v[240:243], v158 offset:512
	ds_read_b128 v[244:247], v158 offset:4096
	ds_read_b128 v[248:251], v158 offset:4608
	v_add_u32_e32 v181, s4, v191
	s_lshl_b32 s35, s34, 7
	s_xor_b32 s4, s4, 0x4000
	s_addk_i32 s35, 0x80
	v_add_u32_e32 v193, s4, v189
	v_add_u32_e32 v194, s4, v188
	s_mov_b64 s[20:21], -1
	s_mov_b32 s36, 0
	s_branch .LBB0_1237
.LBB0_1236:
	ds_read_b128 v[236:239], v158 offset:1024
	ds_read_b128 v[240:243], v158 offset:1536
	ds_read_b128 v[244:247], v158 offset:5120
	ds_read_b128 v[248:251], v158 offset:5632
	v_pk_add_f32 v[76:77], v[170:171], 0 op_sel_hi:[1,0]
	v_pk_add_f32 v[78:79], v[178:179], 0 op_sel_hi:[1,0]
	v_pk_add_f32 v[76:77], v[168:169], v[76:77]
	v_pk_add_f32 v[78:79], v[108:109], v[78:79]
	v_pk_add_f32 v[76:77], v[166:167], v[76:77]
	v_pk_add_f32 v[78:79], v[104:105], v[78:79]
	v_pk_add_f32 v[76:77], v[164:165], v[76:77]
	v_pk_add_f32 v[66:67], v[66:67], v[78:79]
	v_pk_add_f32 v[76:77], v[126:127], v[76:77]
	v_pk_add_f32 v[66:67], v[118:119], v[66:67]
	v_pk_add_f32 v[76:77], v[174:175], v[76:77]
	v_pk_add_f32 v[66:67], v[116:117], v[66:67]
	v_pk_add_f32 v[76:77], v[172:173], v[76:77]
	v_pk_add_f32 v[66:67], v[106:107], v[66:67]
	v_pk_add_f32 v[76:77], v[96:97], v[76:77]
	v_pk_add_f32 v[66:67], v[68:69], v[66:67]
	v_pk_add_f32 v[76:77], v[176:177], v[76:77]
	v_pk_add_f32 v[66:67], v[120:121], v[66:67]
	v_pk_add_f32 v[76:77], v[114:115], v[76:77]
	v_pk_add_f32 v[66:67], v[86:87], v[66:67]
	v_pk_add_f32 v[76:77], v[112:113], v[76:77]
	v_pk_add_f32 v[66:67], v[84:85], v[66:67]
	v_pk_add_f32 v[76:77], v[110:111], v[76:77]
	v_pk_add_f32 v[66:67], v[82:83], v[66:67]
	v_pk_add_f32 v[68:69], v[102:103], v[76:77]
	v_pk_add_f32 v[66:67], v[80:81], v[66:67]
	v_pk_add_f32 v[68:69], v[100:101], v[68:69]
	v_pk_add_f32 v[66:67], v[74:75], v[66:67]
	v_pk_add_f32 v[68:69], v[98:99], v[68:69]
	v_pk_add_f32 v[66:67], v[72:73], v[66:67]
	v_pk_add_f32 v[64:65], v[64:65], v[68:69]
	v_pk_add_f32 v[66:67], v[70:71], v[66:67]
	s_xor_b64 s[4:5], s[20:21], -1
	v_pk_add_f32 v[64:65], v[64:65], v[66:67]
	s_mov_b32 s36, 1
	v_pk_add_f32 v[124:125], v[124:125], v[64:65]
	s_mov_b64 s[20:21], 0
	s_and_b64 vcc, exec, s[4:5]
	s_cbranch_vccnz .LBB0_1241

.LBB0_1239:
	s_lshl_b32 s10, s36, 10
	v_add_u32_e32 v88, s10, v158
	s_lshl_b32 s36, s36, 12
	v_add_u32_e32 v195, s36, v181
	s_waitcnt lgkmcnt(3)
	v_mfma_f32_32x32x16_bf16 v[92:107], v[236:239], v[128:131], 0
	s_and_b64 vcc, exec, s[4:5]
	s_waitcnt lgkmcnt(2)
	v_mfma_f32_32x32x16_bf16 v[64:79], v[240:243], v[128:131], 0
	s_waitcnt lgkmcnt(1)
	v_mfma_f32_32x32x16_bf16 v[92:107], v[244:247], v[132:135], v[92:107]
	s_waitcnt lgkmcnt(0)
	v_mfma_f32_32x32x16_bf16 v[64:79], v[248:251], v[132:135], v[64:79]
	ds_read_b128 v[80:83], v88 offset:8192
	ds_read_b128 v[84:87], v88 offset:8704
	s_nop 7
	v_exp_f32_e32 v171, v92
	v_exp_f32_e32 v169, v93
	v_exp_f32_e32 v167, v94
	v_exp_f32_e32 v165, v95
	v_exp_f32_e32 v127, v96
	v_exp_f32_e32 v175, v97
	s_waitcnt lgkmcnt(1)
	v_mfma_f32_32x32x16_bf16 v[108:123], v[80:83], v[136:139], 0
	ds_read_b128 v[80:83], v88 offset:12288
	ds_read_b128 v[176:179], v88 offset:12800
	v_exp_f32_e32 v173, v98
	v_exp_f32_e32 v97, v99
	v_cvt_pk_bf16_f32 v196, v171, v169
	v_cvt_pk_bf16_f32 v197, v167, v165
	v_cvt_pk_bf16_f32 v198, v127, v175
	v_cvt_pk_bf16_f32 v199, v173, v97
	s_waitcnt lgkmcnt(1)
	v_mfma_f32_32x32x16_bf16 v[108:123], v[80:83], v[140:143], v[108:123]
	ds_read_b64_tr_b16 v[200:201], v195 offset:32768
	ds_read_b64_tr_b16 v[202:203], v195 offset:33280
	ds_read_b64_tr_b16 v[204:205], v195 offset:33792
	ds_read_b64_tr_b16 v[206:207], v195 offset:34304
	ds_read_b64_tr_b16 v[208:209], v195 offset:40960
	ds_read_b64_tr_b16 v[210:211], v195 offset:41472
	v_exp_f32_e32 v99, v106
	ds_read_b64_tr_b16 v[216:217], v195 offset:41984
	ds_read_b64_tr_b16 v[218:219], v195 offset:42496
	v_exp_f32_e32 v67, v67
	s_nop 1
	v_exp_f32_e32 v170, v108
	v_mfma_f32_32x32x16_bf16 v[80:95], v[84:87], v[136:139], 0
	v_exp_f32_e32 v168, v109
	v_exp_f32_e32 v166, v110
	v_exp_f32_e32 v164, v111
	v_exp_f32_e32 v126, v112
	v_exp_f32_e32 v174, v113
	v_exp_f32_e32 v172, v114
	v_exp_f32_e32 v96, v115
	v_cvt_pk_bf16_f32 v212, v170, v168
	v_cvt_pk_bf16_f32 v213, v166, v164
	v_cvt_pk_bf16_f32 v214, v126, v174
	v_cvt_pk_bf16_f32 v215, v172, v96
	s_waitcnt lgkmcnt(8)
	v_mfma_f32_32x32x16_bf16 v[80:95], v[176:179], v[140:143], v[80:95]
	v_exp_f32_e32 v179, v64
	v_exp_f32_e32 v109, v65
	v_exp_f32_e32 v177, v100
	v_exp_f32_e32 v115, v101
	v_exp_f32_e32 v113, v102
	v_exp_f32_e32 v111, v103
	v_exp_f32_e32 v103, v104
	v_exp_f32_e32 v101, v105
	v_exp_f32_e32 v65, v107
	v_exp_f32_e32 v176, v116
	v_exp_f32_e32 v114, v117
	v_exp_f32_e32 v112, v118
	v_exp_f32_e32 v110, v119
	v_exp_f32_e32 v102, v120
	v_exp_f32_e32 v100, v121
	v_exp_f32_e32 v98, v122
	v_exp_f32_e32 v64, v123
	s_waitcnt lgkmcnt(6)
	v_mfma_f32_32x32x16_bf16 v[48:63], v[196:199], v[200:203], v[48:63]
	v_cvt_pk_bf16_f32 v120, v176, v114
	v_cvt_pk_bf16_f32 v121, v112, v110
	v_cvt_pk_bf16_f32 v122, v102, v100
	v_cvt_pk_bf16_f32 v123, v98, v64
	v_exp_f32_e32 v105, v66
	v_exp_f32_e32 v119, v68
	v_exp_f32_e32 v117, v69
	v_mfma_f32_32x32x16_bf16 v[16:31], v[212:215], v[200:203], v[16:31]
	v_exp_f32_e32 v107, v70
	v_exp_f32_e32 v69, v71
	v_exp_f32_e32 v178, v80
	v_exp_f32_e32 v108, v81
	v_exp_f32_e32 v104, v82
	v_exp_f32_e32 v66, v83
	v_exp_f32_e32 v118, v84
	s_waitcnt lgkmcnt(2)
	v_mfma_f32_32x32x16_bf16 v[32:47], v[196:199], v[208:211], v[32:47]
	v_cvt_pk_bf16_f32 v196, v177, v115
	v_cvt_pk_bf16_f32 v197, v113, v111
	v_cvt_pk_bf16_f32 v198, v103, v101
	v_cvt_pk_bf16_f32 v199, v99, v65
	v_exp_f32_e32 v116, v85
	v_exp_f32_e32 v106, v86
	v_exp_f32_e32 v68, v87
	v_mfma_f32_32x32x16_bf16 v[0:15], v[212:215], v[208:211], v[0:15]
	ds_read_b64_tr_b16 v[80:81], v195 offset:34816
	ds_read_b64_tr_b16 v[82:83], v195 offset:35328
	v_cvt_pk_bf16_f32 v208, v178, v108
	v_cvt_pk_bf16_f32 v209, v104, v66
	v_cvt_pk_bf16_f32 v210, v118, v116
	v_cvt_pk_bf16_f32 v211, v106, v68
	ds_read_b64_tr_b16 v[200:201], v195 offset:35840
	ds_read_b64_tr_b16 v[202:203], v195 offset:36352
	v_exp_f32_e32 v87, v73
	v_mfma_f32_32x32x16_bf16 v[48:63], v[196:199], v[204:207], v[48:63]
	v_exp_f32_e32 v85, v74
	v_exp_f32_e32 v73, v78
	v_exp_f32_e32 v71, v79
	v_exp_f32_e32 v86, v89
	v_exp_f32_e32 v84, v90
	v_exp_f32_e32 v74, v93
	v_exp_f32_e32 v70, v95
	v_mfma_f32_32x32x16_bf16 v[16:31], v[120:123], v[204:207], v[16:31]
	ds_read_b64_tr_b16 v[204:205], v195 offset:43008
	ds_read_b64_tr_b16 v[206:207], v195 offset:43520
	ds_read_b64_tr_b16 v[212:213], v195 offset:44032
	ds_read_b64_tr_b16 v[214:215], v195 offset:44544
	v_cvt_pk_bf16_f32 v79, v73, v71
	s_waitcnt lgkmcnt(8)
	v_mfma_f32_32x32x16_bf16 v[32:47], v[196:199], v[216:219], v[32:47]
	v_cvt_pk_bf16_f32 v196, v179, v109
	v_cvt_pk_bf16_f32 v197, v105, v67
	v_cvt_pk_bf16_f32 v198, v119, v117
	v_cvt_pk_bf16_f32 v199, v107, v69
	v_mfma_f32_32x32x16_bf16 v[0:15], v[120:123], v[216:219], v[0:15]
	v_exp_f32_e32 v121, v72
	v_exp_f32_e32 v120, v88
	v_exp_f32_e32 v72, v94
	v_cvt_pk_bf16_f32 v88, v120, v86
	s_waitcnt lgkmcnt(6)
	v_mfma_f32_32x32x16_bf16 v[48:63], v[196:199], v[80:83], v[48:63]
	v_mfma_f32_32x32x16_bf16 v[16:31], v[208:211], v[80:83], v[16:31]
	v_exp_f32_e32 v83, v75
	v_exp_f32_e32 v81, v76
	v_exp_f32_e32 v75, v77
	v_exp_f32_e32 v82, v91
	v_exp_f32_e32 v80, v92
	v_cvt_pk_bf16_f32 v76, v121, v87
	v_cvt_pk_bf16_f32 v77, v85, v83
	s_waitcnt lgkmcnt(2)
	v_mfma_f32_32x32x16_bf16 v[32:47], v[196:199], v[204:207], v[32:47]
	v_cvt_pk_bf16_f32 v78, v81, v75
	v_cvt_pk_bf16_f32 v89, v84, v82
	v_cvt_pk_bf16_f32 v90, v80, v74
	v_cvt_pk_bf16_f32 v91, v72, v70
	v_mfma_f32_32x32x16_bf16 v[0:15], v[208:211], v[204:207], v[0:15]
	v_mfma_f32_32x32x16_bf16 v[48:63], v[76:79], v[200:203], v[48:63]
	s_waitcnt lgkmcnt(0)
	v_mfma_f32_32x32x16_bf16 v[32:47], v[76:79], v[212:215], v[32:47]
	v_mfma_f32_32x32x16_bf16 v[16:31], v[88:91], v[200:203], v[16:31]
	v_mfma_f32_32x32x16_bf16 v[0:15], v[88:91], v[212:215], v[0:15]
	s_cbranch_vccnz .LBB0_1236
	v_add_u32_e32 v77, s10, v194
	v_add_u32_e32 v76, s36, v193
	s_waitcnt vmcnt(1)
	ds_write_b128 v77, v[144:147]
	s_waitcnt vmcnt(0)
	ds_write_b128 v76, v[148:151] offset:32768
	s_branch .LBB0_1236

.LBB0_1255:
	s_lshl_b32 s4, s30, 14
	s_and_b32 s4, s4, 0x4000
	s_cmpk_lg_i32 s30, 0x7f
	s_cselect_b64 s[18:19], -1, 0
	v_add_u32_e32 v158, s4, v190
	ds_read_b128 v[236:239], v158
	ds_read_b128 v[240:243], v158 offset:512
	ds_read_b128 v[244:247], v158 offset:4096
	ds_read_b128 v[248:251], v158 offset:4608
	v_add_u32_e32 v180, s4, v191
	s_lshl_b32 s15, s30, 7
	s_xor_b32 s4, s4, 0x4000
	s_addk_i32 s15, 0x80
	v_add_u32_e32 v181, s4, v189
	v_add_u32_e32 v192, s4, v188
	s_mov_b32 s31, 0
	s_mov_b64 s[20:21], -1
	s_branch .LBB0_1257
.LBB0_1256:
	ds_read_b128 v[236:239], v158 offset:1024
	ds_read_b128 v[240:243], v158 offset:1536
	ds_read_b128 v[244:247], v158 offset:5120
	ds_read_b128 v[248:251], v158 offset:5632
	v_pk_add_f32 v[76:77], v[166:167], 0 op_sel_hi:[1,0]
	v_pk_add_f32 v[78:79], v[176:177], 0 op_sel_hi:[1,0]
	v_pk_add_f32 v[76:77], v[174:175], v[76:77]
	v_pk_add_f32 v[78:79], v[178:179], v[78:79]
	v_pk_add_f32 v[76:77], v[168:169], v[76:77]
	v_pk_add_f32 v[78:79], v[108:109], v[78:79]
	v_pk_add_f32 v[76:77], v[172:173], v[76:77]
	v_pk_add_f32 v[66:67], v[66:67], v[78:79]
	v_pk_add_f32 v[76:77], v[98:99], v[76:77]
	v_pk_add_f32 v[66:67], v[110:111], v[66:67]
	v_pk_add_f32 v[76:77], v[170:171], v[76:77]
	v_pk_add_f32 v[66:67], v[122:123], v[66:67]
	v_pk_add_f32 v[76:77], v[100:101], v[76:77]
	v_pk_add_f32 v[66:67], v[120:121], v[66:67]
	v_pk_add_f32 v[76:77], v[96:97], v[76:77]
	v_pk_add_f32 v[66:67], v[68:69], v[66:67]
	v_pk_add_f32 v[68:69], v[118:119], v[76:77]
	v_pk_add_f32 v[66:67], v[124:125], v[66:67]
	v_pk_add_f32 v[68:69], v[116:117], v[68:69]
	v_pk_add_f32 v[66:67], v[86:87], v[66:67]
	v_pk_add_f32 v[68:69], v[114:115], v[68:69]
	v_pk_add_f32 v[66:67], v[84:85], v[66:67]
	v_pk_add_f32 v[68:69], v[112:113], v[68:69]
	v_pk_add_f32 v[66:67], v[82:83], v[66:67]
	v_pk_add_f32 v[68:69], v[106:107], v[68:69]
	v_pk_add_f32 v[66:67], v[80:81], v[66:67]
	v_pk_add_f32 v[68:69], v[104:105], v[68:69]
	v_pk_add_f32 v[66:67], v[74:75], v[66:67]
	v_pk_add_f32 v[68:69], v[102:103], v[68:69]
	v_pk_add_f32 v[66:67], v[72:73], v[66:67]
	v_pk_add_f32 v[64:65], v[64:65], v[68:69]
	v_pk_add_f32 v[66:67], v[70:71], v[66:67]
	s_xor_b64 s[4:5], s[20:21], -1
	v_pk_add_f32 v[64:65], v[64:65], v[66:67]
	s_mov_b32 s31, 1
	v_pk_add_f32 v[164:165], v[164:165], v[64:65]
	s_mov_b64 s[20:21], 0
	s_and_b64 vcc, exec, s[4:5]
	s_cbranch_vccnz .LBB0_1261

.LBB0_1259:
	s_lshl_b32 s10, s31, 10
	v_add_u32_e32 v88, s10, v158
	s_lshl_b32 s31, s31, 12
	v_add_u32_e32 v193, s31, v180
	s_waitcnt lgkmcnt(3)
	v_mfma_f32_32x32x16_bf16 v[96:111], v[236:239], v[128:131], 0
	s_and_b64 vcc, exec, s[4:5]
	s_waitcnt lgkmcnt(2)
	v_mfma_f32_32x32x16_bf16 v[64:79], v[240:243], v[128:131], 0
	s_waitcnt lgkmcnt(1)
	v_mfma_f32_32x32x16_bf16 v[96:111], v[244:247], v[132:135], v[96:111]
	s_waitcnt lgkmcnt(0)
	v_mfma_f32_32x32x16_bf16 v[64:79], v[248:251], v[132:135], v[64:79]
	ds_read_b128 v[80:83], v88 offset:8192
	ds_read_b128 v[84:87], v88 offset:8704
	s_nop 7
	v_exp_f32_e32 v167, v96
	v_exp_f32_e32 v175, v97
	v_exp_f32_e32 v169, v98
	v_exp_f32_e32 v173, v99
	v_exp_f32_e32 v99, v100
	v_exp_f32_e32 v171, v101
	s_waitcnt lgkmcnt(1)
	v_mfma_f32_32x32x16_bf16 v[112:127], v[80:83], v[136:139], 0
	ds_read_b128 v[80:83], v88 offset:12288
	ds_read_b128 v[176:179], v88 offset:12800
	v_exp_f32_e32 v101, v102
	v_exp_f32_e32 v97, v103
	ds_read_b64_tr_b16 v[194:195], v193 offset:32768
	ds_read_b64_tr_b16 v[196:197], v193 offset:33280
	ds_read_b64_tr_b16 v[198:199], v193 offset:33792
	ds_read_b64_tr_b16 v[200:201], v193 offset:34304
	ds_read_b64_tr_b16 v[202:203], v193 offset:40960
	ds_read_b64_tr_b16 v[204:205], v193 offset:41472
	v_exp_f32_e32 v103, v110
	s_waitcnt lgkmcnt(7)
	v_mfma_f32_32x32x16_bf16 v[112:127], v[80:83], v[140:143], v[112:127]
	ds_read_b64_tr_b16 v[210:211], v193 offset:41984
	ds_read_b64_tr_b16 v[212:213], v193 offset:42496
	v_exp_f32_e32 v67, v67
	v_mfma_f32_32x32x16_bf16 v[80:95], v[84:87], v[136:139], 0
	s_nop 7
	v_exp_f32_e32 v166, v112
	v_exp_f32_e32 v174, v113
	v_exp_f32_e32 v168, v114
	v_exp_f32_e32 v172, v115
	v_exp_f32_e32 v98, v116
	v_exp_f32_e32 v170, v117
	v_exp_f32_e32 v100, v118
	v_exp_f32_e32 v96, v119
	v_cvt_pk_bf16_f32 v112, v167, v175
	v_cvt_pk_bf16_f32 v113, v169, v173
	v_cvt_pk_bf16_f32 v114, v99, v171
	v_cvt_pk_bf16_f32 v115, v101, v97
	v_cvt_pk_bf16_f32 v206, v166, v174
	v_cvt_pk_bf16_f32 v207, v168, v172
	v_cvt_pk_bf16_f32 v208, v98, v170
	v_cvt_pk_bf16_f32 v209, v100, v96
	s_waitcnt lgkmcnt(8)
	v_mfma_f32_32x32x16_bf16 v[80:95], v[176:179], v[140:143], v[80:95]
	v_exp_f32_e32 v179, v65
	v_exp_f32_e32 v119, v104
	v_exp_f32_e32 v117, v105
	v_exp_f32_e32 v105, v109
	v_exp_f32_e32 v65, v111
	v_exp_f32_e32 v177, v64
	v_exp_f32_e32 v118, v120
	s_waitcnt lgkmcnt(6)
	v_mfma_f32_32x32x16_bf16 v[0:15], v[112:115], v[194:197], v[0:15]
	v_exp_f32_e32 v116, v121
	v_exp_f32_e32 v104, v125
	v_exp_f32_e32 v102, v126
	v_exp_f32_e32 v64, v127
	v_exp_f32_e32 v109, v66
	v_exp_f32_e32 v111, v68
	v_exp_f32_e32 v121, v70
	s_waitcnt lgkmcnt(2)
	v_mfma_f32_32x32x16_bf16 v[16:31], v[112:115], v[202:205], v[16:31]
	v_exp_f32_e32 v115, v106
	v_exp_f32_e32 v113, v107
	v_exp_f32_e32 v107, v108
	v_exp_f32_e32 v114, v122
	v_exp_f32_e32 v112, v123
	v_exp_f32_e32 v106, v124
	v_cvt_pk_bf16_f32 v124, v118, v116
	v_mfma_f32_32x32x16_bf16 v[32:47], v[206:209], v[194:197], v[32:47]
	v_cvt_pk_bf16_f32 v194, v119, v117
	v_cvt_pk_bf16_f32 v195, v115, v113
	v_cvt_pk_bf16_f32 v196, v107, v105
	v_cvt_pk_bf16_f32 v197, v103, v65
	v_cvt_pk_bf16_f32 v125, v114, v112
	v_cvt_pk_bf16_f32 v126, v106, v104
	v_cvt_pk_bf16_f32 v127, v102, v64
	v_mfma_f32_32x32x16_bf16 v[48:63], v[206:209], v[202:205], v[48:63]
	v_exp_f32_e32 v123, v69
	v_exp_f32_e32 v69, v71
	v_exp_f32_e32 v176, v80
	v_exp_f32_e32 v178, v81
	v_exp_f32_e32 v108, v82
	v_exp_f32_e32 v66, v83
	v_exp_f32_e32 v110, v84
	v_mfma_f32_32x32x16_bf16 v[0:15], v[194:197], v[198:201], v[0:15]
	v_exp_f32_e32 v122, v85
	v_exp_f32_e32 v120, v86
	v_exp_f32_e32 v68, v87
	v_cvt_pk_bf16_f32 v80, v177, v179
	v_cvt_pk_bf16_f32 v81, v109, v67
	v_cvt_pk_bf16_f32 v82, v111, v123
	v_cvt_pk_bf16_f32 v83, v121, v69
	s_waitcnt lgkmcnt(0)
	v_mfma_f32_32x32x16_bf16 v[16:31], v[194:197], v[210:213], v[16:31]
	ds_read_b64_tr_b16 v[194:195], v193 offset:34816
	ds_read_b64_tr_b16 v[196:197], v193 offset:35328
	v_cvt_pk_bf16_f32 v206, v176, v178
	v_cvt_pk_bf16_f32 v207, v108, v66
	v_cvt_pk_bf16_f32 v208, v110, v122
	v_cvt_pk_bf16_f32 v209, v120, v68
	v_exp_f32_e32 v87, v73
	v_exp_f32_e32 v85, v74
	v_mfma_f32_32x32x16_bf16 v[32:47], v[124:127], v[198:201], v[32:47]
	ds_read_b64_tr_b16 v[198:199], v193 offset:35840
	ds_read_b64_tr_b16 v[200:201], v193 offset:36352
	ds_read_b64_tr_b16 v[202:203], v193 offset:43008
	ds_read_b64_tr_b16 v[204:205], v193 offset:43520
	v_exp_f32_e32 v73, v78
	v_exp_f32_e32 v71, v79
	v_exp_f32_e32 v86, v89
	v_exp_f32_e32 v84, v90
	v_exp_f32_e32 v74, v93
	v_mfma_f32_32x32x16_bf16 v[48:63], v[124:127], v[210:213], v[48:63]
	v_exp_f32_e32 v125, v72
	v_exp_f32_e32 v124, v88
	v_exp_f32_e32 v72, v94
	v_exp_f32_e32 v70, v95
	ds_read_b64_tr_b16 v[210:211], v193 offset:44032
	ds_read_b64_tr_b16 v[212:213], v193 offset:44544
	v_cvt_pk_bf16_f32 v79, v73, v71
	v_cvt_pk_bf16_f32 v88, v124, v86
	s_waitcnt lgkmcnt(6)
	v_mfma_f32_32x32x16_bf16 v[0:15], v[80:83], v[194:197], v[0:15]
	s_waitcnt lgkmcnt(2)
	v_mfma_f32_32x32x16_bf16 v[16:31], v[80:83], v[202:205], v[16:31]
	v_exp_f32_e32 v83, v75
	v_exp_f32_e32 v81, v76
	v_exp_f32_e32 v75, v77
	v_exp_f32_e32 v82, v91
	v_exp_f32_e32 v80, v92
	v_cvt_pk_bf16_f32 v76, v125, v87
	v_cvt_pk_bf16_f32 v77, v85, v83
	v_mfma_f32_32x32x16_bf16 v[32:47], v[206:209], v[194:197], v[32:47]
	v_cvt_pk_bf16_f32 v78, v81, v75
	v_cvt_pk_bf16_f32 v89, v84, v82
	v_cvt_pk_bf16_f32 v90, v80, v74
	v_cvt_pk_bf16_f32 v91, v72, v70
	v_mfma_f32_32x32x16_bf16 v[48:63], v[206:209], v[202:205], v[48:63]
	v_mfma_f32_32x32x16_bf16 v[0:15], v[76:79], v[198:201], v[0:15]
	s_waitcnt lgkmcnt(0)
	v_mfma_f32_32x32x16_bf16 v[16:31], v[76:79], v[210:213], v[16:31]
	v_mfma_f32_32x32x16_bf16 v[32:47], v[88:91], v[198:201], v[32:47]
	v_mfma_f32_32x32x16_bf16 v[48:63], v[88:91], v[210:213], v[48:63]
	s_cbranch_vccnz .LBB0_1256
	v_add_u32_e32 v77, s10, v192
	v_add_u32_e32 v76, s31, v181
	s_waitcnt vmcnt(1)
	ds_write_b128 v77, v[144:147]
	s_waitcnt vmcnt(0)
	ds_write_b128 v76, v[148:151] offset:32768
	s_branch .LBB0_1256
